# SSM pass1/pass2 item->(batch,group,chunk) maps: 128-byte lines of US/YB consumed within one WG / one XCD
# speedup vs baseline: 1.0079x; 1.0010x over previous
; #define LAS __attribute__((address_space(3)))
; __device__ __forceinline__ void ssm_ops_load(SsmOps& S, const float* ABAR, const bf16_t* BBH, const bf16_t* BBL, int g, int lane) {
;     const int fr = lane & 15, fq = lane >> 4; const bf16x8 z = {0, 0, 0, 0, 0, 0, 0, 0};
; #pragma unroll
;     for (int nb = 0; nb < 8; ++nb) { const size_t o = (size_t)(g * 128 + 16 * nb + fr) * 16 + (fq & 1) * 8;
;         const bf16x8 h = *(const bf16x8*)(BBH + o); S.bh[nb] = fq < 2 ? h : z; }
;     S.ar = ABAR[2 * (g * 64 + lane)]; S.ai = ABAR[2 * (g * 64 + lane) + 1];
; }
; __device__ __forceinline__ void ssm_bu_tile(const SsmOps& S, bf16x8 uh, LAS float* tile, int lane) {
;     const int fr = lane & 15, fq = lane >> 4;
;     if (fq >= 2) uh = (bf16x8){0, 0, 0, 0, 0, 0, 0, 0};
; #pragma unroll
;     for (int nb = 0; nb < 8; ++nb) { f32x4 acc = {0.f, 0.f, 0.f, 0.f};
;         acc = __builtin_amdgcn_mfma_f32_16x16x32_bf16(S.bh[nb], uh, acc, 0, 0, 0);
;         *(LAS f32x4*)(tile + fr * TSTR + 16 * nb + 4 * fq) = acc; }
; __device__ __forceinline__ void ssm_pass1(LAS unsigned char* lds, const bf16_t* US, float* SST, const float* ABAR, const bf16_t* BBH, const bf16_t* BBL, int gw, int NGW, int lane, int wave) {
;     ...
;     for (int idx = gw; idx < NB * NG * 7; idx += NGW) {
;         const int c = idx % 7, bg = idx / 7, b = bg >> 5, g = bg & 31;
;         SsmOps S; ssm_ops_load(S, ABAR, BBH, BBL, g, lane);
;         float xr = 0.f, xi = 0.f; const int tokc = b * SEQ + c * 256;
;         bf16x8 uh; ssm_u_load(uh, US, tokc, g, lane);
;         for (int grp = 0; grp < 16; ++grp) {
;             ssm_bu_tile(S, uh, tile, lane);
;             if (grp < 15) ssm_u_load(uh, US, tokc + (grp + 1) * 16, g, lane);
.LBB0_487:
	s_lshr_b32 s16, s3, 9
	s_bfe_u32 s14, s3, 0x30006
	s_bfe_u32 s12, s3, 0x10002
	s_lshl_b32 s14, s14, 1
	s_or_b32 s14, s14, s12
	s_bfe_u32 s12, s3, 0x30003
	s_lshl_b32 s12, s12, 2
	s_and_b32 s15, s3, 3
	s_or_b32 s12, s12, s15
	s_lshl_b32 s14, s14, 5
	s_or_b32 s14, s14, s12
	s_lshl_b32 s17, s14, 6
	s_and_b32 s12, s14, 31
	s_and_b32 s15, s17, 0xfffff800
	s_lshl_b32 s17, s16, 8
	v_lshl_or_b32 v0, s12, 12, v52
	v_lshl_or_b32 v1, s12, 9, v53
	s_add_i32 s17, s15, s17
	global_load_dwordx2 v[40:41], v1, s[0:1]
	global_load_dwordx4 v[4:7], v0, s[10:11]
	global_load_dwordx4 v[8:11], v0, s[10:11] offset:512
	global_load_dwordx4 v[12:15], v0, s[10:11] offset:1024
	global_load_dwordx4 v[16:19], v0, s[10:11] offset:1536
	global_load_dwordx4 v[20:23], v0, s[10:11] offset:2048
	global_load_dwordx4 v[24:27], v0, s[10:11] offset:2560
	global_load_dwordx4 v[56:59], v0, s[10:11] offset:3072
	global_load_dwordx4 v[60:63], v0, s[10:11] offset:3584
	v_or_b32_e32 v0, s17, v48
	v_ashrrev_i32_e32 v1, 31, v0
	v_lshlrev_b64 v[0:1], 10, v[0:1]
	s_lshl_b32 s12, s12, 5
	v_lshl_add_u64 v[0:1], s[46:47], 0, v[0:1]
	v_lshl_add_u64 v[0:1], v[0:1], 0, s[12:13]
	v_lshl_add_u64 v[0:1], v[0:1], 0, v[36:37]
	global_load_dwordx4 v[0:3], v[0:1], off
	v_lshl_add_u64 v[42:43], v[38:39], 0, s[12:13]
	v_or_b32_e32 v55, s17, v51
	s_mov_b32 s12, 0
	v_mov_b32_e32 v46, 0
	v_mov_b32_e32 v47, v37
	s_waitcnt vmcnt(0)
	v_pk_mov_b32 v[44:45], v[40:41], v[40:41] op_sel:[1,0]
	v_cndmask_b32_e32 v7, 0, v7, vcc
	v_cndmask_b32_e32 v6, 0, v6, vcc
	v_cndmask_b32_e32 v5, 0, v5, vcc
	v_cndmask_b32_e32 v4, 0, v4, vcc
	v_cndmask_b32_e32 v11, 0, v11, vcc
	v_cndmask_b32_e32 v10, 0, v10, vcc
	v_cndmask_b32_e32 v9, 0, v9, vcc
	v_cndmask_b32_e32 v8, 0, v8, vcc
	v_cndmask_b32_e32 v15, 0, v15, vcc
	v_cndmask_b32_e32 v14, 0, v14, vcc
	v_cndmask_b32_e32 v13, 0, v13, vcc
	v_cndmask_b32_e32 v12, 0, v12, vcc
	v_cndmask_b32_e32 v19, 0, v19, vcc
	v_cndmask_b32_e32 v18, 0, v18, vcc
	v_cndmask_b32_e32 v17, 0, v17, vcc
	v_cndmask_b32_e32 v16, 0, v16, vcc
	v_cndmask_b32_e32 v31, 0, v23, vcc
	v_cndmask_b32_e32 v30, 0, v22, vcc
	v_cndmask_b32_e32 v29, 0, v21, vcc
	v_cndmask_b32_e32 v28, 0, v20, vcc
	v_cndmask_b32_e32 v35, 0, v27, vcc
	v_cndmask_b32_e32 v34, 0, v26, vcc
	v_cndmask_b32_e32 v33, 0, v25, vcc
	v_cndmask_b32_e32 v32, 0, v24, vcc
	v_cndmask_b32_e32 v27, 0, v59, vcc
	v_cndmask_b32_e32 v26, 0, v58, vcc
	v_cndmask_b32_e32 v25, 0, v57, vcc
	v_cndmask_b32_e32 v24, 0, v56, vcc
	v_cndmask_b32_e32 v23, 0, v63, vcc
	v_cndmask_b32_e32 v22, 0, v62, vcc
	v_cndmask_b32_e32 v21, 0, v61, vcc
	v_cndmask_b32_e32 v20, 0, v60, vcc
	v_readlane_b32 s98, v249, 18
	s_mov_b32 s100, 0x4000
	s_mov_b32 s101, 0
	s_mov_b32 s12, 0
	s_mul_i32 s98, s98, 0x2800
	s_add_i32 s98, s98, 0x8000
	v_lshrrev_b32_e32 v109, 4, v196
	v_mul_u32_u24_e32 v144, 0x50, v48
	v_lshl_add_u32 v144, v109, 4, v144
	v_add_u32_e32 v144, s98, v144
	v_mul_u32_u24_e32 v145, 0x50, v196
	v_add_u32_e32 v145, s98, v145
	v_xor_b32_e32 v77, 0x80000000, v41
	v_mov_b32_e32 v100, 0
	v_mov_b32_e32 v76, 0
	v_lshlrev_b32_e32 v112, 10, v55
	v_mov_b32_e32 v113, 0
	v_lshl_add_u64 v[148:149], v[42:43], 0, v[112:113]
	v_cndmask_b32_e64 v235, v3, 0, s[4:5]
	v_cndmask_b32_e64 v234, v2, 0, s[4:5]
	v_cndmask_b32_e64 v233, v1, 0, s[4:5]
	v_cndmask_b32_e64 v232, v0, 0, s[4:5]
	global_load_dwordx4 v[0:3], v[148:149], off
	v_lshl_add_u64 v[148:149], v[148:149], 0, s[100:101]
	v_mfma_f32_16x16x32_bf16 v[160:163], v[232:235], v[4:7], 0
	v_mfma_f32_16x16x32_bf16 v[164:167], v[232:235], v[8:11], 0
	v_mfma_f32_16x16x32_bf16 v[168:171], v[232:235], v[12:15], 0
	v_mfma_f32_16x16x32_bf16 v[172:175], v[232:235], v[16:19], 0
	v_mfma_f32_16x16x32_bf16 v[176:179], v[232:235], v[28:31], 0
	v_mfma_f32_16x16x32_bf16 v[180:183], v[232:235], v[32:35], 0
	v_mfma_f32_16x16x32_bf16 v[184:187], v[232:235], v[24:27], 0
	v_mfma_f32_16x16x32_bf16 v[188:191], v[232:235], v[20:23], 0
	s_nop 0
	ds_write_b128 v144, v[160:163]
	ds_write_b128 v144, v[164:167] offset:1280
	ds_write_b128 v144, v[168:171] offset:2560
	ds_write_b128 v144, v[172:175] offset:3840
	ds_write_b128 v144, v[176:179] offset:5120
	ds_write_b128 v144, v[180:183] offset:6400
	ds_write_b128 v144, v[184:187] offset:7680
	ds_write_b128 v144, v[188:191] offset:8960

; __device__ __forceinline__ void ssm_pass2(LAS unsigned char* lds, const bf16_t* US, const float* SST, bf16_t* YB, const float* ABAR, const bf16_t* BBH, const bf16_t* BBL, const bf16_t* CMH, const bf16_t* CML, const float* dco, int gw, int NGW, int lane, int wave) {
;     ...
;     for (int idx = gw; idx < NB * NG * 8; idx += NGW) {
;         const int c = idx & 7, bg = idx >> 3, b = bg >> 5, g = bg & 31;
;         SsmOps S; ssm_ops_load(S, ABAR, BBH, BBL, g, lane);
;         bf16x8 ch[4];
; #pragma unroll
;         for (int ks = 0; ks < 4; ++ks) { const size_t o = (size_t)(g * 16 + fr) * 128 + ks * 32 + fq * 8; ch[ks] = *(const bf16x8*)(CMH + o); }
;         const float dh = dco[g * 16 + fr];
;         float pr = S.ar, pi = S.ai;
; #pragma unroll
;         for (int s = 0; s < 8; ++s) { const float nr = pr * pr - pi * pi, ni = 2.f * pr * pi; pr = nr; pi = ni; }
;         float xr = 0.f, xi = 0.f;
;         { float sr[7], sm[7];
; #pragma unroll
;           for (int cc = 0; cc < 7; ++cc) { const float* si = SST + ((size_t)bg * 8 + (cc < c ? cc : 0)) * 128; sr[cc] = si[lane]; sm[cc] = si[64 + lane]; }
; #pragma unroll
;           for (int cc = 0; cc < 7; ++cc) if (cc < c) { const float nr = pr * xr - pi * xi + sr[cc], ni = pr * xi + pi * xr + sm[cc]; xr = nr; xi = ni; } }
.LBB0_547:
	s_ashr_i32 s72, s70, 3
	s_and_b32 s20, s72, 31
	s_and_b32 s21, s20, 7
	s_lshl_b32 s21, s21, 2
	s_lshr_b32 s20, s20, 3
	s_or_b32 s20, s20, s21
	s_andn2_b32 s72, s72, 31
	s_or_b32 s72, s72, s20
	s_lshl_b32 s21, s20, 11
	v_or_b32_e32 v0, s21, v115
	v_lshlrev_b32_e32 v0, 1, v0
	v_or_b32_e32 v1, s21, v116
	global_load_dwordx4 v[16:19], v0, s[52:53]
	global_load_dwordx4 v[20:23], v0, s[52:53] offset:512
	global_load_dwordx4 v[24:27], v0, s[52:53] offset:1024
	global_load_dwordx4 v[28:31], v0, s[52:53] offset:1536
	global_load_dwordx4 v[32:35], v0, s[52:53] offset:2048
	global_load_dwordx4 v[36:39], v0, s[52:53] offset:2560
	global_load_dwordx4 v[40:43], v0, s[52:53] offset:3072
	global_load_dwordx4 v[44:47], v0, s[52:53] offset:3584
	v_lshl_or_b32 v0, s20, 9, v122
	v_lshlrev_b32_e32 v1, 1, v1
	global_load_dwordx2 v[90:91], v0, s[50:51]
	global_load_dwordx4 v[12:15], v1, s[54:55]
	global_load_dwordx4 v[8:11], v1, s[54:55] offset:64
	global_load_dwordx4 v[4:7], v1, s[54:55] offset:128
	s_nop 0
	global_load_dwordx4 v[0:3], v1, s[54:55] offset:192
	s_lshl_b32 s20, s20, 4
	v_or_b32_e32 v48, s20, v114
	s_ashr_i32 s73, s72, 31
	v_lshlrev_b32_e32 v48, 2, v48
	s_lshl_b64 s[72:73], s[72:73], 12
	global_load_dword v124, v48, s[38:39]
	v_lshl_add_u64 v[48:49], v[82:83], 0, s[72:73]
	s_mov_b32 s61, s57
	v_lshl_add_u64 v[52:53], v[48:49], 0, s[56:57]
	s_mov_b32 s59, s57
	v_lshl_add_u64 v[56:57], v[48:49], 0, s[60:61]
	s_mov_b32 s63, s57
	v_lshl_add_u64 v[54:55], v[48:49], 0, s[58:59]
	v_lshl_add_u64 v[58:59], v[48:49], 0, s[62:63]
	global_load_dword v50, v[52:53], off
	global_load_dword v64, v[52:53], off offset:256
	global_load_dword v62, v[54:55], off
	global_load_dword v63, v[54:55], off offset:256
	global_load_dword v60, v[56:57], off
	global_load_dword v61, v[56:57], off offset:256
	s_nop 0
	global_load_dword v56, v[58:59], off
	global_load_dword v57, v[58:59], off offset:256
	s_mov_b32 s65, s57
	v_lshl_add_u64 v[52:53], v[48:49], 0, s[64:65]
	s_mov_b32 s67, s57
	v_lshl_add_u64 v[66:67], v[48:49], 0, s[66:67]
	global_load_dword v58, v[52:53], off
	global_load_dword v59, v[52:53], off offset:256
	global_load_dword v54, v[66:67], off
	global_load_dword v55, v[66:67], off offset:256
	v_mov_b32_e32 v52, 0
	s_andn2_b64 vcc, exec, s[34:35]
	s_waitcnt vmcnt(0)
	v_pk_mul_f32 v[66:67], v[90:91], v[90:91]
	v_add_f32_e32 v51, v90, v90
	v_sub_f32_e32 v53, v66, v67
	v_mul_f32_e32 v51, v91, v51
	v_mul_f32_e32 v65, v53, v53
	v_add_f32_e32 v53, v53, v53
	v_fma_f32 v65, -v51, v51, v65
	v_mul_f32_e32 v51, v51, v53
	v_mul_f32_e32 v53, v51, v51
	v_add_f32_e32 v66, v65, v65
	v_fma_f32 v53, v65, v65, -v53
	v_mul_f32_e32 v51, v51, v66
	v_mul_f32_e32 v65, v51, v51
	v_add_f32_e32 v66, v53, v53
	v_fma_f32 v53, v53, v53, -v65
	v_mul_f32_e32 v51, v51, v66
	v_mul_f32_e32 v65, v51, v51
	v_add_f32_e32 v66, v53, v53
	v_fma_f32 v53, v53, v53, -v65
	v_mul_f32_e32 v51, v51, v66
	v_mul_f32_e32 v65, v51, v51
	v_add_f32_e32 v66, v53, v53
	v_fma_f32 v53, v53, v53, -v65
	v_mul_f32_e32 v51, v51, v66
	v_mul_f32_e32 v65, v51, v51
	v_add_f32_e32 v66, v53, v53
	v_fma_f32 v53, v53, v53, -v65
	v_mul_f32_e32 v51, v51, v66
	v_mul_f32_e32 v65, v51, v51
	v_add_f32_e32 v66, v53, v53
	v_fma_f32 v65, v53, v53, -v65
	v_mul_f32_e32 v66, v51, v66
	v_mov_b32_e32 v53, 0
	s_cbranch_vccnz .LBB0_549
	global_load_dword v52, v[48:49], off offset:256
	global_load_dword v53, v[48:49], off
	v_mul_f32_e32 v48, 0, v65
	v_mul_f32_e32 v49, 0, v66
	v_add_f32_e32 v48, v48, v49
	v_fma_f32 v49, v65, 0, -v49
	s_waitcnt vmcnt(0)
	v_pk_add_f32 v[52:53], v[48:49], v[52:53]
